# chain: the 9 per-wave LDS-DMA pieces of the next step spread between the first 17 MFMAs of the step instead of issued back to back at the step top
# baseline (speedup 1.0000x reference)
; #define LAS __attribute__((address_space(3)))
; #define RD_QD(dst, s0) _Pragma("unroll") for (int s_ = 0; s_ < 4; ++s_) { dst[s_] = *(const LAS bf16x8*)(B + CH_QD + i0 * 256 + (((2 * ((s0) + s_) + hi) ^ (i0 & 15)) << 4)); \
;                 dst[4 + s_] = *(const LAS bf16x8*)(B + CH_QD + i1 * 256 + (((2 * ((s0) + s_) + hi) ^ (i1 & 15)) << 4)); }
; #define DECAY(db_) do { f32x4 dc_[4]; _Pragma("unroll") for (int a4_ = 0; a4_ < 4; ++a4_) dc_[a4_] = *(const LAS f32x4*)(B + CH_DEC + ((db_) * 32 + 8 * a4_ + 4 * hi) * 4); \
;                 _Pragma("unroll") for (int a4_ = 0; a4_ < 4; ++a4_) _Pragma("unroll") for (int b4_ = 0; b4_ < 4; ++b4_) T[db_][a4_ * 4 + b4_] *= dc_[a4_][b4_]; } while (0)
; DI void phase_gla_chain(const Params& P, int l, int task0, int ntask_stride, LAS unsigned char* lds) {
;     ...
;             RD_QD(fa, 0);
; #pragma unroll
;             for (int ks = 0; ks < 4; ++ks) vf[ks] = *(const LAS bf16x8*)(B + CH_VT + vv * 128 + (((2 * ks + hi) ^ ((vv >> 1) & 7)) << 4));
;             __builtin_amdgcn_sched_barrier(0);
;             RD_QD(fb, 4);
;             __builtin_amdgcn_sched_barrier(0);
;             MM_QD(fa, 0);
;             DECAY(0); DECAY(1);
;             __builtin_amdgcn_sched_barrier(0);
; #pragma unroll
;             for (int ks = 0; ks < 4; ++ks) { fa[ks] = *(const LAS bf16x8*)(B + CH_AM + i0 * 128 + (((2 * ks + hi) ^ ((i0 >> 1) & 7)) << 4)); fa[4 + ks] = *(const LAS bf16x8*)(B + CH_AM + i1 * 128 + (((2 * ks + hi) ^ ((i1 >> 1) & 7)) << 4)); }
;             __builtin_amdgcn_sched_barrier(0);
;             MM_QD(fb, 4);
;             DECAY(2); DECAY(3);
;             __builtin_amdgcn_sched_barrier(0);
.LBB0_409:
	s_mul_i32 s92, s92, 0x12400
	s_add_i32 s22, s92, 0
	v_add_u32_e32 v74, s22, v205
	v_add_u32_e32 v75, s22, v141
	v_add_u32_e32 v66, v74, v149
	v_add_u32_e32 v70, v75, v149
	v_add_u32_e32 v76, v74, v151
	ds_read_b128 v[66:69], v66
	ds_read_b128 v[70:73], v70
	v_add_u32_e32 v77, v75, v151
	ds_read_b128 v[182:185], v76
	ds_read_b128 v[186:189], v77
	v_add_u32_e32 v76, v74, v153
	v_add_u32_e32 v77, v75, v153
	ds_read_b128 v[190:193], v76
	ds_read_b128 v[194:197], v77
	v_add_u32_e32 v76, v74, v160
	v_add_u32_e32 v77, v75, v160
	ds_read_b128 v[198:201], v76
	ds_read_b128 v[208:211], v77
	v_add_u32_e32 v76, s22, v173
	v_add_u32_e32 v77, v76, v162
	v_add_u32_e32 v78, v76, v164
	ds_read_b128 v[110:113], v77 offset:40960
	ds_read_b128 v[106:109], v78 offset:40960
	v_add_u32_e32 v77, v76, v165
	v_add_u32_e32 v76, v76, v166
	ds_read_b128 v[102:105], v77 offset:40960
	ds_read_b128 v[98:101], v76 offset:40960
	v_add_u32_e32 v76, v74, v167
	v_add_u32_e32 v77, v75, v167
	ds_read_b128 v[212:215], v76
	ds_read_b128 v[216:219], v77
	v_add_u32_e32 v76, v74, v168
	v_add_u32_e32 v77, v75, v168
	ds_read_b128 v[220:223], v76
	ds_read_b128 v[130:133], v77
	v_add_u32_e32 v76, v74, v169
	v_add_u32_e32 v74, v74, v170
	v_add_u32_e32 v77, v75, v169
	ds_read_b128 v[126:129], v76
	ds_read_b128 v[122:125], v77
	v_add_u32_e32 v75, v75, v170
	ds_read_b128 v[118:121], v74
	ds_read_b128 v[114:117], v75
	v_cvt_pk_bf16_f32 v74, v2, v3
	v_cvt_pk_bf16_f32 v75, v4, v5
	v_cvt_pk_bf16_f32 v76, v6, v7
	v_cvt_pk_bf16_f32 v77, v8, v9
	v_cvt_pk_bf16_f32 v224, v10, v11
	v_cvt_pk_bf16_f32 v225, v12, v13
	s_waitcnt lgkmcnt(0)
	v_mfma_f32_32x32x16_bf16 v[82:97], v[66:69], v[74:77], 0
	s_cmp_eq_u32 s8, -1
	s_cbranch_scc1 .Lsp_0_0
	s_add_i32 m0, s99, 0x0
	s_nop 0
	global_load_lds_dwordx4 v134, s[100:101] nt
.Lsp_0_0:
	v_cvt_pk_bf16_f32 v226, v14, v15
	v_cvt_pk_bf16_f32 v227, v16, v17
	v_add_u32_e32 v207, s22, v146
	v_add_u32_e32 v231, 0x12000, v207
	v_cvt_pk_bf16_f32 v228, v26, v27
	v_cvt_pk_bf16_f32 v229, v28, v29
	v_cvt_pk_bf16_f32 v230, v30, v31
	v_mfma_f32_32x32x16_bf16 v[66:81], v[70:73], v[74:77], 0
	v_mfma_f32_32x32x16_bf16 v[82:97], v[182:185], v[224:227], v[82:97]
	s_cmp_eq_u32 s8, -1
	s_cbranch_scc1 .Lsp_0_1
	s_add_i32 m0, s99, 0x400
	s_nop 0
	global_load_lds_dwordx4 v245, s[100:101] nt
.Lsp_0_1:
	v_cvt_pk_bf16_f32 v182, v18, v19
	v_cvt_pk_bf16_f32 v183, v20, v21
	v_cvt_pk_bf16_f32 v184, v22, v23
	v_cvt_pk_bf16_f32 v185, v24, v25
	v_mfma_f32_32x32x16_bf16 v[66:81], v[186:189], v[224:227], v[66:81]
	ds_read_b128 v[186:189], v231 offset:64
	ds_read_b128 v[224:227], v231 offset:96
	ds_read_b128 v[232:235], v231
	ds_read_b128 v[236:239], v231 offset:32
	v_cvt_pk_bf16_f32 v231, v32, v33
	s_waitcnt lgkmcnt(0)
	v_pk_mul_f32 v[10:11], v[10:11], v[186:187]
	v_pk_mul_f32 v[12:13], v[12:13], v[188:189]
	v_pk_mul_f32 v[14:15], v[14:15], v[224:225]
	v_pk_mul_f32 v[6:7], v[6:7], v[236:237]
	v_pk_mul_f32 v[16:17], v[16:17], v[226:227]
	v_mfma_f32_32x32x16_bf16 v[82:97], v[190:193], v[182:185], v[82:97]
	s_cmp_eq_u32 s8, -1
	s_cbranch_scc1 .Lsp_0_2
	s_add_i32 m0, s99, 0x800
	s_nop 0
	global_load_lds_dwordx4 v246, s[100:101] nt
.Lsp_0_2:
	v_mul_f32_e64 v8, v8, v238
	v_mul_f32_e64 v9, v9, v239
	v_mul_f32_e64 v4, v4, v234
	v_mul_f32_e64 v5, v5, v235
	v_mul_f32_e64 v2, v2, v232
	v_mul_f32_e64 v3, v3, v233
	v_mfma_f32_32x32x16_bf16 v[66:81], v[194:197], v[182:185], v[66:81]
	v_add_u32_e32 v194, 0x12080, v207
	ds_read_b128 v[182:185], v194 offset:64
	ds_read_b128 v[186:189], v194 offset:96
	ds_read_b128 v[190:193], v194
	ds_read_b128 v[194:197], v194 offset:32
	s_waitcnt lgkmcnt(0)
	v_pk_mul_f32 v[26:27], v[26:27], v[182:183]
	v_pk_mul_f32 v[30:31], v[30:31], v[186:187]
	v_pk_mul_f32 v[32:33], v[32:33], v[188:189]
	v_pk_mul_f32 v[22:23], v[22:23], v[194:195]
	v_pk_mul_f32 v[28:29], v[28:29], v[184:185]
	v_pk_mul_f32 v[24:25], v[24:25], v[196:197]
	v_pk_mul_f32 v[20:21], v[20:21], v[192:193]
	v_pk_mul_f32 v[18:19], v[18:19], v[190:191]
	v_mfma_f32_32x32x16_bf16 v[82:97], v[198:201], v[228:231], v[82:97]
	s_cmp_eq_u32 s8, -1
	s_cbranch_scc1 .Lsp_0_3
	s_add_i32 m0, s99, 0xc00
	s_nop 0
	global_load_lds_dwordx4 v247, s[100:101] nt
.Lsp_0_3:
	v_mfma_f32_32x32x16_bf16 v[66:81], v[208:211], v[228:231], v[66:81]
	v_add_u32_e32 v224, s22, v143
	v_add_u32_e32 v225, s22, v145
	v_add_u32_e32 v240, v224, v162
	v_add_u32_e32 v186, v225, v162
	v_add_u32_e32 v241, v224, v164
	v_add_u32_e32 v194, v225, v164
	v_add_u32_e32 v242, v224, v165
	v_add_u32_e32 v208, v225, v165
	v_add_u32_e32 v243, v224, v166
	v_add_u32_e32 v228, v225, v166
	ds_read_b128 v[182:185], v240 offset:16384
	ds_read_b128 v[186:189], v186 offset:16384
	ds_read_b128 v[190:193], v241 offset:16384
	ds_read_b128 v[194:197], v194 offset:16384
	ds_read_b128 v[198:201], v242 offset:16384
	ds_read_b128 v[208:211], v208 offset:16384
	ds_read_b128 v[224:227], v243 offset:16384
	ds_read_b128 v[228:231], v228 offset:16384
	v_cvt_pk_bf16_f32 v232, v34, v35
	v_cvt_pk_bf16_f32 v233, v36, v37
	v_cvt_pk_bf16_f32 v234, v38, v39
	v_cvt_pk_bf16_f32 v235, v40, v41
	s_nop 1
	v_mfma_f32_32x32x16_bf16 v[82:97], v[212:215], v[232:235], v[82:97]
	s_cmp_eq_u32 s8, -1
	s_cbranch_scc1 .Lsp_0_4
	s_add_i32 m0, s99, 0x1000
	s_nop 0
	global_load_lds_dwordx4 v248, s[100:101] nt
.Lsp_0_4:
	v_cvt_pk_bf16_f32 v212, v42, v43
	v_cvt_pk_bf16_f32 v213, v44, v45
	v_cvt_pk_bf16_f32 v214, v46, v47
	v_cvt_pk_bf16_f32 v215, v48, v49
	v_mfma_f32_32x32x16_bf16 v[66:81], v[216:219], v[232:235], v[66:81]
	v_cvt_pk_bf16_f32 v216, v50, v51
	v_cvt_pk_bf16_f32 v217, v52, v53
	v_cvt_pk_bf16_f32 v218, v54, v55
	v_cvt_pk_bf16_f32 v219, v56, v57
	v_mfma_f32_32x32x16_bf16 v[82:97], v[220:223], v[212:215], v[82:97]
	s_cmp_eq_u32 s8, -1
	s_cbranch_scc1 .Lsp_0_5
	s_add_i32 m0, s65, 0xa000
	s_nop 0
	global_load_lds_dwordx4 v134, s[66:67] nt
; DI int crow(int r, int hi) { return (r & 3) + 8 * (r >> 2) + 4 * hi; }
; DI unsigned pkbf(float a, float b) { f32x2 v = {a, b}; bfx2 r = __builtin_convertvector(v, bfx2); return __builtin_bit_cast(unsigned, r); }
; #define RD_KT(dst, db0) _Pragma("unroll") for (int q_ = 0; q_ < 2; ++q_) { const int d_ = ((db0) + q_) * 32 + r32; \
;                 _Pragma("unroll") for (int ks_ = 0; ks_ < 4; ++ks_) dst[q_ * 4 + ks_] = *(const LAS bf16x8*)(B + CH_KT + d_ * 128 + (((2 * ks_ + hi) ^ ((d_ >> 1) & 7)) << 4)); }
; #define MM_KT(src, db0) _Pragma("unroll") for (int q_ = 0; q_ < 2; ++q_) { \
;                 _Pragma("unroll") for (int ks_ = 0; ks_ < 4; ++ks_) T[(db0) + q_] = __builtin_amdgcn_mfma_f32_32x32x16_bf16(src[q_ * 4 + ks_], vf[ks_], T[(db0) + q_], 0, 0, 0); }
; DI void phase_gla_chain(const Params& P, int l, int task0, int ntask_stride, LAS unsigned char* lds) {
;     ...
;             MM_QD(fb, 4);
;             DECAY(2); DECAY(3);
;             __builtin_amdgcn_sched_barrier(0);
;             RD_KT(fb, 0);
;             __builtin_amdgcn_sched_barrier(0);
; #pragma unroll
;             for (int ks = 0; ks < 4; ++ks) { o[0] = __builtin_amdgcn_mfma_f32_32x32x16_bf16(fa[ks], vf[ks], o[0], 0, 0, 0); o[1] = __builtin_amdgcn_mfma_f32_32x32x16_bf16(fa[4 + ks], vf[ks], o[1], 0, 0, 0); }
;             __builtin_amdgcn_sched_barrier(0);
;             RD_KT(fa, 2);
;             __builtin_amdgcn_sched_barrier(0);
;             MM_KT(fb, 0);
;             __builtin_amdgcn_sched_barrier(0);
;             MM_KT(fa, 2);
;     ...
;             { const int cs = dir ? 63 - n : n; const size_t tokb = (size_t)sq * SEQL + cs * 64; const int odd = lane & 1;
;               bf16_t* ob = OFB + (size_t)dir * MTOK * 1024 + h * 256 + wid * 32 + (r32 & ~1);
; #pragma unroll
;               for (int ib = 0; ib < 2; ++ib)
; #pragma unroll
;                   for (int x = 0; x < 16; x += 2) { float ea_ = o[ib][x], eb_ = o[ib][x + 1]; asm volatile("" : "+v"(ea_), "+v"(eb_)); const float mine = odd ? eb_ : ea_, give = odd ? ea_ : eb_;
;                       const float got = __int_as_float(__builtin_amdgcn_update_dpp(0, __float_as_int(give), 0xB1, 0xF, 0xF, true));
;                       const unsigned w = odd ? pkbf(got, mine) : pkbf(mine, got);
;                       *(unsigned*)(ob + (tokb + ib * 32 + crow(x + odd, hi)) * 1024) = w; } }
.Lsp_0_5:
	v_add_u32_e32 v223, 0x12100, v207
	v_add_u32_e32 v207, 0x12180, v207
	v_cvt_pk_bf16_f32 v220, v58, v59
	v_cvt_pk_bf16_f32 v221, v60, v61
	v_cvt_pk_bf16_f32 v222, v62, v63
	v_mfma_f32_32x32x16_bf16 v[66:81], v[130:133], v[212:215], v[66:81]
	ds_read_b128 v[130:133], v223 offset:64
	ds_read_b128 v[212:215], v223 offset:96
	ds_read_b128 v[232:235], v223
	ds_read_b128 v[236:239], v223 offset:32
	v_cvt_pk_bf16_f32 v223, v64, v65
	s_waitcnt lgkmcnt(0)
	v_pk_mul_f32 v[42:43], v[42:43], v[130:131]
	v_pk_mul_f32 v[46:47], v[46:47], v[212:213]
	v_pk_mul_f32 v[48:49], v[48:49], v[214:215]
	v_pk_mul_f32 v[44:45], v[44:45], v[132:133]
	v_pk_mul_f32 v[38:39], v[38:39], v[236:237]
	v_mfma_f32_32x32x16_bf16 v[82:97], v[126:129], v[216:219], v[82:97]
	s_cmp_eq_u32 s8, -1
	s_cbranch_scc1 .Lsp_0_6
	s_add_i32 m0, s65, 0xa400
	s_nop 0
	global_load_lds_dwordx4 v245, s[66:67] nt
.Lsp_0_6:
	v_mul_f32_e64 v40, v40, v238
	v_mul_f32_e64 v41, v41, v239
	v_mul_f32_e64 v36, v36, v234
	v_mul_f32_e64 v37, v37, v235
	v_mul_f32_e64 v34, v34, v232
	v_mul_f32_e64 v35, v35, v233
	v_mfma_f32_32x32x16_bf16 v[66:81], v[122:125], v[216:219], v[66:81]
	ds_read_b128 v[122:125], v207 offset:64
	ds_read_b128 v[126:129], v207 offset:96
	ds_read_b128 v[130:133], v207
	ds_read_b128 v[212:215], v207 offset:32
	s_waitcnt lgkmcnt(0)
	v_pk_mul_f32 v[58:59], v[58:59], v[122:123]
	v_pk_mul_f32 v[62:63], v[62:63], v[126:127]
	v_pk_mul_f32 v[64:65], v[64:65], v[128:129]
	v_pk_mul_f32 v[54:55], v[54:55], v[212:213]
	v_pk_mul_f32 v[60:61], v[60:61], v[124:125]
	v_pk_mul_f32 v[56:57], v[56:57], v[214:215]
	v_pk_mul_f32 v[52:53], v[52:53], v[132:133]
	v_pk_mul_f32 v[50:51], v[50:51], v[130:131]
	v_mfma_f32_32x32x16_bf16 v[82:97], v[118:121], v[220:223], v[82:97]
	s_cmp_eq_u32 s8, -1
	s_cbranch_scc1 .Lsp_0_7
	s_add_i32 m0, s65, 0xa800
	s_nop 0
	global_load_lds_dwordx4 v246, s[66:67] nt
.Lsp_0_7:
	v_mfma_f32_32x32x16_bf16 v[66:81], v[114:117], v[220:223], v[66:81]
	ds_read_b128 v[114:117], v240 offset:24576
	ds_read_b128 v[118:121], v240 offset:28672
	ds_read_b128 v[122:125], v241 offset:24576
	ds_read_b128 v[126:129], v241 offset:28672
	ds_read_b128 v[130:133], v242 offset:24576
	ds_read_b128 v[212:215], v242 offset:28672
	ds_read_b128 v[216:219], v243 offset:24576
	ds_read_b128 v[220:223], v243 offset:28672
	v_mfma_f32_32x32x16_bf16 v[82:97], v[182:185], v[110:113], v[82:97]
	s_cmp_eq_u32 s8, -1
	s_cbranch_scc1 .Lsp_0_8
	s_add_i32 m0, s65, 0xac00
	s_nop 0
	global_load_lds_dwordx4 v247, s[66:67] nt
.Lsp_0_8:
	v_mfma_f32_32x32x16_bf16 v[66:81], v[186:189], v[110:113], v[66:81]
	v_mfma_f32_32x32x16_bf16 v[82:97], v[190:193], v[106:109], v[82:97]
	v_mfma_f32_32x32x16_bf16 v[66:81], v[194:197], v[106:109], v[66:81]
	v_mfma_f32_32x32x16_bf16 v[82:97], v[198:201], v[102:105], v[82:97]
	v_mfma_f32_32x32x16_bf16 v[66:81], v[208:211], v[102:105], v[66:81]
	v_mfma_f32_32x32x16_bf16 v[82:97], v[224:227], v[98:101], v[82:97]
	v_mfma_f32_32x32x16_bf16 v[66:81], v[228:231], v[98:101], v[66:81]
	ds_read_b128 v[182:185], v240 offset:32768
	ds_read_b128 v[186:189], v240 offset:36864
	ds_read_b128 v[190:193], v241 offset:32768
	ds_read_b128 v[194:197], v241 offset:36864
	ds_read_b128 v[198:201], v242 offset:32768
	ds_read_b128 v[208:211], v242 offset:36864
	ds_read_b128 v[224:227], v243 offset:32768
	ds_read_b128 v[228:231], v243 offset:36864
	s_waitcnt lgkmcnt(0)
	v_mfma_f32_32x32x16_bf16 v[2:17], v[114:117], v[110:113], v[2:17]
	v_mfma_f32_32x32x16_bf16 v[18:33], v[118:121], v[110:113], v[18:33]
	v_mfma_f32_32x32x16_bf16 v[2:17], v[122:125], v[106:109], v[2:17]
	v_mfma_f32_32x32x16_bf16 v[18:33], v[126:129], v[106:109], v[18:33]
	v_mfma_f32_32x32x16_bf16 v[2:17], v[130:133], v[102:105], v[2:17]
	v_mfma_f32_32x32x16_bf16 v[18:33], v[212:215], v[102:105], v[18:33]
	v_mfma_f32_32x32x16_bf16 v[2:17], v[216:219], v[98:101], v[2:17]
	v_mfma_f32_32x32x16_bf16 v[18:33], v[220:223], v[98:101], v[18:33]
	s_add_i32 s64, s8, 1
	s_and_b64 s[22:23], s[10:11], exec
	s_cselect_b32 s22, s91, s64
	s_lshl_b32 s22, s22, 6
	s_add_u32 s23, s20, s22
	v_cndmask_b32_e64 v114, v82, v83, s[0:1]
	s_addc_u32 s22, s21, 0
	v_mfma_f32_32x32x16_bf16 v[34:49], v[182:185], v[110:113], v[34:49]
	v_mov_b32_dpp v114, v114 quad_perm:[1,0,3,2] row_mask:0xf bank_mask:0xf bound_ctrl:1
	v_cndmask_b32_e64 v83, v83, v114, s[0:1]
	v_cndmask_b32_e64 v82, v114, v82, s[0:1]
	v_cvt_pk_bf16_f32 v114, v82, v83
	v_readfirstlane_b32 s98, v158
	v_readfirstlane_b32 s99, v159
	v_and_b32_e32 v244, 30, v137
	v_lshlrev_b32_e32 v244, 1, v244
	v_lshl_add_u32 v244, v136, 11, v244
	s_lshl_b32 s100, s23, 11
	s_add_u32 s98, s98, s100
	s_addc_u32 s99, s99, 0
	s_add_u32 s100, s98, 0x800
	s_addc_u32 s101, s99, 0
	global_store_dword v244, v114, s[100:101] offset:-2048
	v_mov_b32_e32 v82, v84
	v_mfma_f32_32x32x16_bf16 v[50:65], v[186:189], v[110:113], v[50:65]
	v_cndmask_b32_e64 v83, v82, v85, s[0:1]
	s_add_i32 s8, s8, -1
	s_add_i32 s90, s90, 1
	v_mov_b32_dpp v83, v83 quad_perm:[1,0,3,2] row_mask:0xf bank_mask:0xf bound_ctrl:1
	v_cndmask_b32_e64 v84, v85, v83, s[0:1]
	v_cndmask_b32_e64 v82, v83, v82, s[0:1]
	v_cvt_pk_bf16_f32 v84, v82, v84
	global_store_dword v244, v84, s[100:101] offset:2048
	v_mov_b32_e32 v82, v87
	v_mfma_f32_32x32x16_bf16 v[34:49], v[190:193], v[106:109], v[34:49]
	v_cndmask_b32_e64 v83, v86, v82, s[0:1]
	s_nop 1
	v_mov_b32_dpp v83, v83 quad_perm:[1,0,3,2] row_mask:0xf bank_mask:0xf bound_ctrl:1
	v_cndmask_b32_e64 v82, v82, v83, s[0:1]
	v_cndmask_b32_e64 v83, v83, v86, s[0:1]
	v_cvt_pk_bf16_f32 v84, v83, v82
	s_add_u32 s100, s98, 0x4800
	s_addc_u32 s101, s99, 0
	global_store_dword v244, v84, s[100:101] offset:-2048
	v_mov_b32_e32 v82, v88
; DI int crow(int r, int hi) { return (r & 3) + 8 * (r >> 2) + 4 * hi; }
; DI unsigned pkbf(float a, float b) { f32x2 v = {a, b}; bfx2 r = __builtin_convertvector(v, bfx2); return __builtin_bit_cast(unsigned, r); }
; DI void phase_gla_chain(const Params& P, int l, int task0, int ntask_stride, LAS unsigned char* lds) {
;     ...
;         __syncthreads();
;         CH_ISSUE(0, 0);
;         for (int n = 0; n < 64; ++n) {
;             const int b = n & 1;
;             if (n == 0) asm volatile("s_waitcnt vmcnt(0)" ::: "memory"); else asm volatile("s_waitcnt vmcnt(16)" ::: "memory");
;             __builtin_amdgcn_s_barrier();
;             asm volatile("" ::: "memory");
;             if (n + 1 < 64) CH_ISSUE(n + 1, b ^ 1);
;     ...
;             { const int cs = dir ? 63 - n : n; const size_t tokb = (size_t)sq * SEQL + cs * 64; const int odd = lane & 1;
;               bf16_t* ob = OFB + (size_t)dir * MTOK * 1024 + h * 256 + wid * 32 + (r32 & ~1);
; #pragma unroll
;               for (int ib = 0; ib < 2; ++ib)
; #pragma unroll
;                   for (int x = 0; x < 16; x += 2) { float ea_ = o[ib][x], eb_ = o[ib][x + 1]; asm volatile("" : "+v"(ea_), "+v"(eb_)); const float mine = odd ? eb_ : ea_, give = odd ? ea_ : eb_;
;                       const float got = __int_as_float(__builtin_amdgcn_update_dpp(0, __float_as_int(give), 0xB1, 0xF, 0xF, true));
;                       const unsigned w = odd ? pkbf(got, mine) : pkbf(mine, got);
;                       *(unsigned*)(ob + (tokb + ib * 32 + crow(x + odd, hi)) * 1024) = w; } }
	v_mfma_f32_32x32x16_bf16 v[50:65], v[194:197], v[106:109], v[50:65]
	v_cndmask_b32_e64 v83, v82, v89, s[0:1]
	s_nop 1
	v_mov_b32_dpp v83, v83 quad_perm:[1,0,3,2] row_mask:0xf bank_mask:0xf bound_ctrl:1
	v_cndmask_b32_e64 v84, v89, v83, s[0:1]
	v_cndmask_b32_e64 v82, v83, v82, s[0:1]
	v_cvt_pk_bf16_f32 v84, v82, v84
	global_store_dword v244, v84, s[100:101] offset:2048
	v_mov_b32_e32 v82, v90
	v_mfma_f32_32x32x16_bf16 v[34:49], v[198:201], v[102:105], v[34:49]
	v_cndmask_b32_e64 v83, v82, v91, s[0:1]
	s_nop 1
	v_mov_b32_dpp v83, v83 quad_perm:[1,0,3,2] row_mask:0xf bank_mask:0xf bound_ctrl:1
	v_cndmask_b32_e64 v84, v91, v83, s[0:1]
	v_cndmask_b32_e64 v82, v83, v82, s[0:1]
	v_cvt_pk_bf16_f32 v84, v82, v84
	s_add_u32 s100, s98, 0x8800
	s_addc_u32 s101, s99, 0
	global_store_dword v244, v84, s[100:101] offset:-2048
	v_mov_b32_e32 v82, v93
	v_mfma_f32_32x32x16_bf16 v[50:65], v[208:211], v[102:105], v[50:65]
	v_cndmask_b32_e64 v83, v92, v82, s[0:1]
	s_nop 1
	v_mov_b32_dpp v83, v83 quad_perm:[1,0,3,2] row_mask:0xf bank_mask:0xf bound_ctrl:1
	v_cndmask_b32_e64 v82, v82, v83, s[0:1]
	v_cndmask_b32_e64 v83, v83, v92, s[0:1]
	v_cvt_pk_bf16_f32 v84, v83, v82
	global_store_dword v244, v84, s[100:101] offset:2048
	v_mov_b32_e32 v82, v94
	v_mfma_f32_32x32x16_bf16 v[34:49], v[224:227], v[98:101], v[34:49]
	v_cndmask_b32_e64 v83, v82, v95, s[0:1]
	s_nop 1
	v_mov_b32_dpp v83, v83 quad_perm:[1,0,3,2] row_mask:0xf bank_mask:0xf bound_ctrl:1
	v_cndmask_b32_e64 v84, v95, v83, s[0:1]
	v_cndmask_b32_e64 v82, v83, v82, s[0:1]
	v_cvt_pk_bf16_f32 v84, v82, v84
	s_add_u32 s100, s98, 0xc800
	s_addc_u32 s101, s99, 0
	global_store_dword v244, v84, s[100:101] offset:-2048
	v_mov_b32_e32 v82, v96
	v_mfma_f32_32x32x16_bf16 v[50:65], v[228:231], v[98:101], v[50:65]
	v_cndmask_b32_e64 v83, v82, v97, s[0:1]
	s_nop 1
	v_mov_b32_dpp v83, v83 quad_perm:[1,0,3,2] row_mask:0xf bank_mask:0xf bound_ctrl:1
	v_cndmask_b32_e64 v84, v97, v83, s[0:1]
	v_cndmask_b32_e64 v82, v83, v82, s[0:1]
	v_cvt_pk_bf16_f32 v84, v82, v84
	global_store_dword v244, v84, s[100:101] offset:2048
	s_or_b32 s23, s23, 32
	v_cndmask_b32_e64 v82, v66, v67, s[0:1]
	s_nop 0
	v_mov_b32_dpp v82, v82 quad_perm:[1,0,3,2] row_mask:0xf bank_mask:0xf bound_ctrl:1
	v_cndmask_b32_e64 v67, v67, v82, s[0:1]
	v_cndmask_b32_e64 v66, v82, v66, s[0:1]
	v_cvt_pk_bf16_f32 v82, v66, v67
	s_add_u32 s100, s98, 0x10800
	s_addc_u32 s101, s99, 0
	global_store_dword v244, v82, s[100:101] offset:-2048
	v_mov_b32_e32 v66, v68
	s_nop 0
	v_cndmask_b32_e64 v67, v66, v69, s[0:1]
	s_nop 1
	v_mov_b32_dpp v67, v67 quad_perm:[1,0,3,2] row_mask:0xf bank_mask:0xf bound_ctrl:1
	v_cndmask_b32_e64 v68, v69, v67, s[0:1]
	v_cndmask_b32_e64 v66, v67, v66, s[0:1]
	v_cvt_pk_bf16_f32 v68, v66, v68
	global_store_dword v244, v68, s[100:101] offset:2048
	v_mov_b32_e32 v66, v70
	s_nop 0
	v_cndmask_b32_e64 v67, v66, v71, s[0:1]
	s_nop 1
	v_mov_b32_dpp v67, v67 quad_perm:[1,0,3,2] row_mask:0xf bank_mask:0xf bound_ctrl:1
	v_cndmask_b32_e64 v68, v71, v67, s[0:1]
	v_cndmask_b32_e64 v66, v67, v66, s[0:1]
	v_cvt_pk_bf16_f32 v68, v66, v68
	s_add_u32 s100, s98, 0x14800
	s_addc_u32 s101, s99, 0
	global_store_dword v244, v68, s[100:101] offset:-2048
	v_mov_b32_e32 v66, v73
	s_nop 0
	v_cndmask_b32_e64 v67, v72, v66, s[0:1]
	s_nop 1
	v_mov_b32_dpp v67, v67 quad_perm:[1,0,3,2] row_mask:0xf bank_mask:0xf bound_ctrl:1
	v_cndmask_b32_e64 v66, v66, v67, s[0:1]
	v_cndmask_b32_e64 v67, v67, v72, s[0:1]
	v_cvt_pk_bf16_f32 v68, v67, v66
	global_store_dword v244, v68, s[100:101] offset:2048
	v_mov_b32_e32 v66, v74
	s_nop 0
	v_cndmask_b32_e64 v67, v66, v75, s[0:1]
	s_nop 1
	v_mov_b32_dpp v67, v67 quad_perm:[1,0,3,2] row_mask:0xf bank_mask:0xf bound_ctrl:1
	v_cndmask_b32_e64 v68, v75, v67, s[0:1]
	v_cndmask_b32_e64 v66, v67, v66, s[0:1]
	v_cvt_pk_bf16_f32 v68, v66, v68
	s_add_u32 s100, s98, 0x18800
	s_addc_u32 s101, s99, 0
	global_store_dword v244, v68, s[100:101] offset:-2048
	v_mov_b32_e32 v66, v76
	s_nop 0
	v_cndmask_b32_e64 v67, v66, v77, s[0:1]
	s_nop 1
	v_mov_b32_dpp v67, v67 quad_perm:[1,0,3,2] row_mask:0xf bank_mask:0xf bound_ctrl:1
	v_cndmask_b32_e64 v68, v77, v67, s[0:1]
	v_cndmask_b32_e64 v66, v67, v66, s[0:1]
	v_cvt_pk_bf16_f32 v68, v66, v68
	global_store_dword v244, v68, s[100:101] offset:2048
	v_mov_b32_e32 v66, v79
	s_nop 0
	v_cndmask_b32_e64 v67, v78, v66, s[0:1]
	s_nop 1
	v_mov_b32_dpp v67, v67 quad_perm:[1,0,3,2] row_mask:0xf bank_mask:0xf bound_ctrl:1
	v_cndmask_b32_e64 v66, v66, v67, s[0:1]
	v_cndmask_b32_e64 v67, v67, v78, s[0:1]
	v_cvt_pk_bf16_f32 v68, v67, v66
	s_add_u32 s100, s98, 0x1c800
	s_addc_u32 s101, s99, 0
	global_store_dword v244, v68, s[100:101] offset:-2048
	v_mov_b32_e32 v66, v81
	s_nop 0
	v_cndmask_b32_e64 v67, v80, v66, s[0:1]
	s_nop 1
	v_mov_b32_dpp v67, v67 quad_perm:[1,0,3,2] row_mask:0xf bank_mask:0xf bound_ctrl:1
	v_cndmask_b32_e64 v66, v66, v67, s[0:1]
	v_cndmask_b32_e64 v67, v67, v80, s[0:1]
	v_cvt_pk_bf16_f32 v68, v67, v66
	global_store_dword v244, v68, s[100:101] offset:2048
	s_cmp_eq_u32 s8, -2
	s_cbranch_scc1 .LBB0_403
.LBB0_410:
	s_add_i32 s91, s90, -1
	s_waitcnt vmcnt(16)
	s_barrier
	s_and_b32 s92, s91, 1
	s_cmp_eq_u32 s8, -1
	s_cbranch_scc1 .LBB0_409
	s_and_b64 s[22:23], s[10:11], exec
	s_cselect_b32 s22, s90, s8
	s_add_i32 s22, s22, s89
	s_lshl_b32 s22, s22, 2
	s_or_b32 s96, s22, s88
	s_ashr_i32 s97, s96, 31
	s_add_u32 s22, s25, s96
	s_addc_u32 s23, 0, s97
	s_mul_i32 s93, s23, 0xa000
	s_mul_hi_u32 vcc_lo, s22, 0xa000
	s_add_i32 vcc_lo, vcc_lo, s93
	s_mul_i32 s93, s22, 0xa000
	s_add_u32 vcc_hi, s27, s93
	s_addc_u32 vcc_lo, s28, vcc_lo
	s_lshl_b64 s[96:97], s[96:97], 15
	s_add_u32 s68, s29, s96
	s_addc_u32 s69, s30, s97
	s_xor_b32 s93, s92, 1
	s_mul_i32 s93, s93, 0x12400
	s_add_i32 s93, s93, 0
	v_add_u32_e32 v245, 0x400, v134
	v_add_u32_e32 v246, 0x800, v134
	v_add_u32_e32 v247, 0xc00, v134
	v_add_u32_e32 v248, 0x1000, v134
	s_lshl_b32 s32, s31, 4
	s_lshl_b32 s98, s31, 2
	s_add_i32 s98, s98, s32
	s_add_u32 s100, vcc_hi, s98
	s_addc_u32 s101, vcc_lo, 0
	s_add_i32 s99, s93, s98
	s_add_u32 s66, s68, s32
	s_addc_u32 s67, s69, 0
	s_add_i32 s65, s93, s32
	s_and_b64 vcc, exec, s[2:3]
	s_cbranch_vccnz .LBB0_409
	s_add_i32 s64, s93, s31
	s_lshl_b64 s[22:23], s[22:23], 9
	s_add_i32 m0, s64, 0x12000
	v_lshl_add_u64 v[66:67], v[156:157], 0, s[22:23]
	global_load_lds_dword v[66:67], off
	s_branch .LBB0_409

; #define LAS __attribute__((address_space(3)))
; #define RD_QD(dst, s0) _Pragma("unroll") for (int s_ = 0; s_ < 4; ++s_) { dst[s_] = *(const LAS bf16x8*)(B + CH_QD + i0 * 256 + (((2 * ((s0) + s_) + hi) ^ (i0 & 15)) << 4)); \
;                 dst[4 + s_] = *(const LAS bf16x8*)(B + CH_QD + i1 * 256 + (((2 * ((s0) + s_) + hi) ^ (i1 & 15)) << 4)); }
; #define DECAY(db_) do { f32x4 dc_[4]; _Pragma("unroll") for (int a4_ = 0; a4_ < 4; ++a4_) dc_[a4_] = *(const LAS f32x4*)(B + CH_DEC + ((db_) * 32 + 8 * a4_ + 4 * hi) * 4); \
;                 _Pragma("unroll") for (int a4_ = 0; a4_ < 4; ++a4_) _Pragma("unroll") for (int b4_ = 0; b4_ < 4; ++b4_) T[db_][a4_ * 4 + b4_] *= dc_[a4_][b4_]; } while (0)
; DI void phase_gla_chain(const Params& P, int l, int task0, int ntask_stride, LAS unsigned char* lds) {
;     ...
;             RD_QD(fa, 0);
; #pragma unroll
;             for (int ks = 0; ks < 4; ++ks) vf[ks] = *(const LAS bf16x8*)(B + CH_VT + vv * 128 + (((2 * ks + hi) ^ ((vv >> 1) & 7)) << 4));
;             __builtin_amdgcn_sched_barrier(0);
;             RD_QD(fb, 4);
;             __builtin_amdgcn_sched_barrier(0);
;             MM_QD(fa, 0);
;             DECAY(0); DECAY(1);
;             __builtin_amdgcn_sched_barrier(0);
; #pragma unroll
;             for (int ks = 0; ks < 4; ++ks) { fa[ks] = *(const LAS bf16x8*)(B + CH_AM + i0 * 128 + (((2 * ks + hi) ^ ((i0 >> 1) & 7)) << 4)); fa[4 + ks] = *(const LAS bf16x8*)(B + CH_AM + i1 * 128 + (((2 * ks + hi) ^ ((i1 >> 1) & 7)) << 4)); }
;             __builtin_amdgcn_sched_barrier(0);
;             MM_QD(fb, 4);
;             DECAY(2); DECAY(3);
;             __builtin_amdgcn_sched_barrier(0);
.LBB0_971:
	s_mul_i32 s84, s84, 0x12400
	s_add_i32 s22, s84, 0
	v_add_u32_e32 v74, s22, v201
	v_add_u32_e32 v75, s22, v141
	v_add_u32_e32 v66, v74, v149
	v_add_u32_e32 v70, v75, v149
	v_add_u32_e32 v76, v74, v151
	ds_read_b128 v[66:69], v66
	ds_read_b128 v[70:73], v70
	v_add_u32_e32 v77, v75, v151
	ds_read_b128 v[182:185], v76
	ds_read_b128 v[186:189], v77
	v_add_u32_e32 v76, v74, v153
	v_add_u32_e32 v77, v75, v153
	ds_read_b128 v[190:193], v76
	ds_read_b128 v[194:197], v77
	v_add_u32_e32 v76, v74, v160
	v_add_u32_e32 v77, v75, v160
	ds_read_b128 v[204:207], v76
	ds_read_b128 v[208:211], v77
	v_add_u32_e32 v76, s22, v173
	v_add_u32_e32 v77, v76, v162
	v_add_u32_e32 v78, v76, v164
	ds_read_b128 v[110:113], v77 offset:40960
	ds_read_b128 v[106:109], v78 offset:40960
	v_add_u32_e32 v77, v76, v165
	v_add_u32_e32 v76, v76, v166
	ds_read_b128 v[102:105], v77 offset:40960
	ds_read_b128 v[98:101], v76 offset:40960
	v_add_u32_e32 v76, v74, v167
	v_add_u32_e32 v77, v75, v167
	ds_read_b128 v[212:215], v76
	ds_read_b128 v[216:219], v77
	v_add_u32_e32 v76, v74, v168
	v_add_u32_e32 v77, v75, v168
	ds_read_b128 v[220:223], v76
	ds_read_b128 v[130:133], v77
	v_add_u32_e32 v76, v74, v169
	v_add_u32_e32 v74, v74, v170
	v_add_u32_e32 v77, v75, v169
	ds_read_b128 v[126:129], v76
	ds_read_b128 v[122:125], v77
	v_add_u32_e32 v75, v75, v170
	ds_read_b128 v[118:121], v74
	ds_read_b128 v[114:117], v75
	v_cvt_pk_bf16_f32 v74, v2, v3
	v_cvt_pk_bf16_f32 v75, v4, v5
	v_cvt_pk_bf16_f32 v76, v6, v7
	v_cvt_pk_bf16_f32 v77, v8, v9
	v_cvt_pk_bf16_f32 v224, v10, v11
	v_cvt_pk_bf16_f32 v225, v12, v13
	s_waitcnt lgkmcnt(0)
	v_mfma_f32_32x32x16_bf16 v[82:97], v[66:69], v[74:77], 0
	s_cmp_eq_u32 s8, -1
	s_cbranch_scc1 .Lsp_1_0
	s_add_i32 m0, s99, 0x0
	s_nop 0
	global_load_lds_dwordx4 v134, s[100:101] nt
.Lsp_1_0:
	v_cvt_pk_bf16_f32 v226, v14, v15
	v_cvt_pk_bf16_f32 v227, v16, v17
	v_add_u32_e32 v198, s22, v146
	v_add_u32_e32 v199, 0x12000, v198
	v_cvt_pk_bf16_f32 v228, v26, v27
	v_cvt_pk_bf16_f32 v229, v28, v29
	v_cvt_pk_bf16_f32 v230, v30, v31
	v_mfma_f32_32x32x16_bf16 v[66:81], v[70:73], v[74:77], 0
	v_cvt_pk_bf16_f32 v231, v32, v33
	v_mfma_f32_32x32x16_bf16 v[82:97], v[182:185], v[224:227], v[82:97]
	s_cmp_eq_u32 s8, -1
	s_cbranch_scc1 .Lsp_1_1
	s_add_i32 m0, s99, 0x400
	s_nop 0
	global_load_lds_dwordx4 v245, s[100:101] nt
.Lsp_1_1:
	v_cvt_pk_bf16_f32 v182, v18, v19
	v_cvt_pk_bf16_f32 v183, v20, v21
	v_cvt_pk_bf16_f32 v184, v22, v23
	v_cvt_pk_bf16_f32 v185, v24, v25
	v_mfma_f32_32x32x16_bf16 v[66:81], v[186:189], v[224:227], v[66:81]
	ds_read_b128 v[186:189], v199 offset:64
	ds_read_b128 v[224:227], v199 offset:96
	ds_read_b128 v[232:235], v199
	ds_read_b128 v[236:239], v199 offset:32
	s_waitcnt lgkmcnt(0)
	v_pk_mul_f32 v[10:11], v[10:11], v[186:187]
	v_pk_mul_f32 v[12:13], v[12:13], v[188:189]
	v_pk_mul_f32 v[14:15], v[14:15], v[224:225]
	v_pk_mul_f32 v[6:7], v[6:7], v[236:237]
	v_pk_mul_f32 v[16:17], v[16:17], v[226:227]
	v_mfma_f32_32x32x16_bf16 v[82:97], v[190:193], v[182:185], v[82:97]
	s_cmp_eq_u32 s8, -1
	s_cbranch_scc1 .Lsp_1_2
	s_add_i32 m0, s99, 0x800
	s_nop 0
	global_load_lds_dwordx4 v246, s[100:101] nt
.Lsp_1_2:
	v_mul_f32_e64 v8, v8, v238
	v_mul_f32_e64 v9, v9, v239
	v_mul_f32_e64 v4, v4, v234
	v_mul_f32_e64 v5, v5, v235
	v_mul_f32_e64 v2, v2, v232
	v_mul_f32_e64 v3, v3, v233
	v_mfma_f32_32x32x16_bf16 v[66:81], v[194:197], v[182:185], v[66:81]
	v_add_u32_e32 v194, 0x12080, v198
	ds_read_b128 v[182:185], v194 offset:64
	ds_read_b128 v[186:189], v194 offset:96
	ds_read_b128 v[190:193], v194
	ds_read_b128 v[194:197], v194 offset:32
	s_waitcnt lgkmcnt(0)
	v_pk_mul_f32 v[26:27], v[26:27], v[182:183]
	v_pk_mul_f32 v[30:31], v[30:31], v[186:187]
	v_pk_mul_f32 v[32:33], v[32:33], v[188:189]
	v_pk_mul_f32 v[22:23], v[22:23], v[194:195]
	v_pk_mul_f32 v[28:29], v[28:29], v[184:185]
	v_pk_mul_f32 v[24:25], v[24:25], v[196:197]
	v_pk_mul_f32 v[20:21], v[20:21], v[192:193]
	v_pk_mul_f32 v[18:19], v[18:19], v[190:191]
	v_mfma_f32_32x32x16_bf16 v[82:97], v[204:207], v[228:231], v[82:97]
	s_cmp_eq_u32 s8, -1
	s_cbranch_scc1 .Lsp_1_3
	s_add_i32 m0, s99, 0xc00
	s_nop 0
	global_load_lds_dwordx4 v247, s[100:101] nt
.Lsp_1_3:
	v_mfma_f32_32x32x16_bf16 v[66:81], v[208:211], v[228:231], v[66:81]
	v_add_u32_e32 v199, s22, v143
	v_add_u32_e32 v224, s22, v145
	v_add_u32_e32 v240, v199, v162
	v_add_u32_e32 v186, v224, v162
	v_add_u32_e32 v241, v199, v164
	v_add_u32_e32 v194, v224, v164
	v_add_u32_e32 v242, v199, v165
	v_add_u32_e32 v208, v224, v165
	v_add_u32_e32 v199, v199, v166
	v_add_u32_e32 v228, v224, v166
	ds_read_b128 v[182:185], v240 offset:16384
	ds_read_b128 v[186:189], v186 offset:16384
	ds_read_b128 v[190:193], v241 offset:16384
	ds_read_b128 v[194:197], v194 offset:16384
	ds_read_b128 v[204:207], v242 offset:16384
	ds_read_b128 v[208:211], v208 offset:16384
	ds_read_b128 v[224:227], v199 offset:16384
	ds_read_b128 v[228:231], v228 offset:16384
	v_cvt_pk_bf16_f32 v232, v34, v35
	v_cvt_pk_bf16_f32 v233, v36, v37
	v_cvt_pk_bf16_f32 v234, v38, v39
	v_cvt_pk_bf16_f32 v235, v40, v41
	s_nop 1
	v_mfma_f32_32x32x16_bf16 v[82:97], v[212:215], v[232:235], v[82:97]
	s_cmp_eq_u32 s8, -1
	s_cbranch_scc1 .Lsp_1_4
	s_add_i32 m0, s99, 0x1000
	s_nop 0
	global_load_lds_dwordx4 v248, s[100:101] nt
.Lsp_1_4:
	v_cvt_pk_bf16_f32 v212, v42, v43
	v_cvt_pk_bf16_f32 v213, v44, v45
	v_cvt_pk_bf16_f32 v214, v46, v47
	v_cvt_pk_bf16_f32 v215, v48, v49
	v_mfma_f32_32x32x16_bf16 v[66:81], v[216:219], v[232:235], v[66:81]
	v_cvt_pk_bf16_f32 v216, v50, v51
	v_cvt_pk_bf16_f32 v217, v52, v53
	v_cvt_pk_bf16_f32 v218, v54, v55
	v_cvt_pk_bf16_f32 v219, v56, v57
	v_mfma_f32_32x32x16_bf16 v[82:97], v[220:223], v[212:215], v[82:97]
	s_cmp_eq_u32 s8, -1
	s_cbranch_scc1 .Lsp_1_5
	s_add_i32 m0, s90, 0xa000
	s_nop 0
	global_load_lds_dwordx4 v134, s[88:89] nt
; DI int crow(int r, int hi) { return (r & 3) + 8 * (r >> 2) + 4 * hi; }
; DI unsigned pkbf(float a, float b) { f32x2 v = {a, b}; bfx2 r = __builtin_convertvector(v, bfx2); return __builtin_bit_cast(unsigned, r); }
; #define RD_KT(dst, db0) _Pragma("unroll") for (int q_ = 0; q_ < 2; ++q_) { const int d_ = ((db0) + q_) * 32 + r32; \
;                 _Pragma("unroll") for (int ks_ = 0; ks_ < 4; ++ks_) dst[q_ * 4 + ks_] = *(const LAS bf16x8*)(B + CH_KT + d_ * 128 + (((2 * ks_ + hi) ^ ((d_ >> 1) & 7)) << 4)); }
; #define MM_KT(src, db0) _Pragma("unroll") for (int q_ = 0; q_ < 2; ++q_) { \
;                 _Pragma("unroll") for (int ks_ = 0; ks_ < 4; ++ks_) T[(db0) + q_] = __builtin_amdgcn_mfma_f32_32x32x16_bf16(src[q_ * 4 + ks_], vf[ks_], T[(db0) + q_], 0, 0, 0); }
; DI void phase_gla_chain(const Params& P, int l, int task0, int ntask_stride, LAS unsigned char* lds) {
;     ...
;             MM_QD(fb, 4);
;             DECAY(2); DECAY(3);
;             __builtin_amdgcn_sched_barrier(0);
;             RD_KT(fb, 0);
;             __builtin_amdgcn_sched_barrier(0);
; #pragma unroll
;             for (int ks = 0; ks < 4; ++ks) { o[0] = __builtin_amdgcn_mfma_f32_32x32x16_bf16(fa[ks], vf[ks], o[0], 0, 0, 0); o[1] = __builtin_amdgcn_mfma_f32_32x32x16_bf16(fa[4 + ks], vf[ks], o[1], 0, 0, 0); }
;             __builtin_amdgcn_sched_barrier(0);
;             RD_KT(fa, 2);
;             __builtin_amdgcn_sched_barrier(0);
;             MM_KT(fb, 0);
;             __builtin_amdgcn_sched_barrier(0);
;             MM_KT(fa, 2);
;     ...
;             { const int cs = dir ? 63 - n : n; const size_t tokb = (size_t)sq * SEQL + cs * 64; const int odd = lane & 1;
;               bf16_t* ob = OFB + (size_t)dir * MTOK * 1024 + h * 256 + wid * 32 + (r32 & ~1);
; #pragma unroll
;               for (int ib = 0; ib < 2; ++ib)
; #pragma unroll
;                   for (int x = 0; x < 16; x += 2) { float ea_ = o[ib][x], eb_ = o[ib][x + 1]; asm volatile("" : "+v"(ea_), "+v"(eb_)); const float mine = odd ? eb_ : ea_, give = odd ? ea_ : eb_;
;                       const float got = __int_as_float(__builtin_amdgcn_update_dpp(0, __float_as_int(give), 0xB1, 0xF, 0xF, true));
;                       const unsigned w = odd ? pkbf(got, mine) : pkbf(mine, got);
;                       *(unsigned*)(ob + (tokb + ib * 32 + crow(x + odd, hi)) * 1024) = w; } }
.Lsp_1_5:
	v_add_u32_e32 v223, 0x12100, v198
	v_add_u32_e32 v198, 0x12180, v198
	v_cvt_pk_bf16_f32 v220, v58, v59
	v_cvt_pk_bf16_f32 v221, v60, v61
	v_cvt_pk_bf16_f32 v222, v62, v63
	v_mfma_f32_32x32x16_bf16 v[66:81], v[130:133], v[212:215], v[66:81]
	ds_read_b128 v[130:133], v223 offset:64
	ds_read_b128 v[212:215], v223 offset:96
	ds_read_b128 v[232:235], v223
	ds_read_b128 v[236:239], v223 offset:32
	v_cvt_pk_bf16_f32 v223, v64, v65
	s_waitcnt lgkmcnt(0)
	v_pk_mul_f32 v[42:43], v[42:43], v[130:131]
	v_pk_mul_f32 v[46:47], v[46:47], v[212:213]
	v_pk_mul_f32 v[48:49], v[48:49], v[214:215]
	v_pk_mul_f32 v[44:45], v[44:45], v[132:133]
	v_pk_mul_f32 v[38:39], v[38:39], v[236:237]
	v_mfma_f32_32x32x16_bf16 v[82:97], v[126:129], v[216:219], v[82:97]
	s_cmp_eq_u32 s8, -1
	s_cbranch_scc1 .Lsp_1_6
	s_add_i32 m0, s90, 0xa400
	s_nop 0
	global_load_lds_dwordx4 v245, s[88:89] nt
.Lsp_1_6:
	v_mul_f32_e64 v40, v40, v238
	v_mul_f32_e64 v41, v41, v239
	v_mul_f32_e64 v36, v36, v234
	v_mul_f32_e64 v37, v37, v235
	v_mul_f32_e64 v34, v34, v232
	v_mul_f32_e64 v35, v35, v233
	v_mfma_f32_32x32x16_bf16 v[66:81], v[122:125], v[216:219], v[66:81]
	ds_read_b128 v[122:125], v198 offset:64
	ds_read_b128 v[126:129], v198 offset:96
	ds_read_b128 v[130:133], v198
	ds_read_b128 v[212:215], v198 offset:32
	s_waitcnt lgkmcnt(0)
	v_pk_mul_f32 v[58:59], v[58:59], v[122:123]
	v_pk_mul_f32 v[62:63], v[62:63], v[126:127]
	v_pk_mul_f32 v[64:65], v[64:65], v[128:129]
	v_pk_mul_f32 v[54:55], v[54:55], v[212:213]
	v_pk_mul_f32 v[60:61], v[60:61], v[124:125]
	v_pk_mul_f32 v[56:57], v[56:57], v[214:215]
	v_pk_mul_f32 v[52:53], v[52:53], v[132:133]
	v_pk_mul_f32 v[50:51], v[50:51], v[130:131]
	v_mfma_f32_32x32x16_bf16 v[82:97], v[118:121], v[220:223], v[82:97]
	s_cmp_eq_u32 s8, -1
	s_cbranch_scc1 .Lsp_1_7
	s_add_i32 m0, s90, 0xa800
	s_nop 0
	global_load_lds_dwordx4 v246, s[88:89] nt
.Lsp_1_7:
	v_mfma_f32_32x32x16_bf16 v[66:81], v[114:117], v[220:223], v[66:81]
	ds_read_b128 v[114:117], v240 offset:24576
	ds_read_b128 v[118:121], v240 offset:28672
	ds_read_b128 v[122:125], v241 offset:24576
	ds_read_b128 v[126:129], v241 offset:28672
	ds_read_b128 v[130:133], v242 offset:24576
	ds_read_b128 v[212:215], v242 offset:28672
	ds_read_b128 v[216:219], v199 offset:24576
	ds_read_b128 v[220:223], v199 offset:28672
	v_mfma_f32_32x32x16_bf16 v[82:97], v[182:185], v[110:113], v[82:97]
	s_cmp_eq_u32 s8, -1
	s_cbranch_scc1 .Lsp_1_8
	s_add_i32 m0, s90, 0xac00
	s_nop 0
	global_load_lds_dwordx4 v247, s[88:89] nt
.Lsp_1_8:
	v_mfma_f32_32x32x16_bf16 v[66:81], v[186:189], v[110:113], v[66:81]
	v_mfma_f32_32x32x16_bf16 v[82:97], v[190:193], v[106:109], v[82:97]
	v_mfma_f32_32x32x16_bf16 v[66:81], v[194:197], v[106:109], v[66:81]
	v_mfma_f32_32x32x16_bf16 v[82:97], v[204:207], v[102:105], v[82:97]
	v_mfma_f32_32x32x16_bf16 v[66:81], v[208:211], v[102:105], v[66:81]
	v_mfma_f32_32x32x16_bf16 v[82:97], v[224:227], v[98:101], v[82:97]
	v_mfma_f32_32x32x16_bf16 v[66:81], v[228:231], v[98:101], v[66:81]
	ds_read_b128 v[182:185], v240 offset:32768
	ds_read_b128 v[186:189], v240 offset:36864
	ds_read_b128 v[190:193], v241 offset:32768
	ds_read_b128 v[194:197], v241 offset:36864
	ds_read_b128 v[204:207], v242 offset:32768
	ds_read_b128 v[208:211], v242 offset:36864
	ds_read_b128 v[224:227], v199 offset:32768
	ds_read_b128 v[228:231], v199 offset:36864
	s_waitcnt lgkmcnt(0)
	v_mfma_f32_32x32x16_bf16 v[2:17], v[114:117], v[110:113], v[2:17]
	v_mfma_f32_32x32x16_bf16 v[18:33], v[118:121], v[110:113], v[18:33]
	v_mfma_f32_32x32x16_bf16 v[2:17], v[122:125], v[106:109], v[2:17]
	v_mfma_f32_32x32x16_bf16 v[18:33], v[126:129], v[106:109], v[18:33]
	v_mfma_f32_32x32x16_bf16 v[2:17], v[130:133], v[102:105], v[2:17]
	v_mfma_f32_32x32x16_bf16 v[18:33], v[212:215], v[102:105], v[18:33]
	v_mfma_f32_32x32x16_bf16 v[2:17], v[216:219], v[98:101], v[2:17]
	v_mfma_f32_32x32x16_bf16 v[18:33], v[220:223], v[98:101], v[18:33]
	s_add_i32 s64, s8, 1
	s_and_b64 s[22:23], s[10:11], exec
	s_cselect_b32 s22, s83, s64
	s_lshl_b32 s22, s22, 6
	s_add_u32 s23, s20, s22
	v_cndmask_b32_e64 v114, v82, v83, s[0:1]
	s_addc_u32 s22, s21, 0
	v_mfma_f32_32x32x16_bf16 v[34:49], v[182:185], v[110:113], v[34:49]
	v_mov_b32_dpp v114, v114 quad_perm:[1,0,3,2] row_mask:0xf bank_mask:0xf bound_ctrl:1
	v_cndmask_b32_e64 v83, v83, v114, s[0:1]
	v_cndmask_b32_e64 v82, v114, v82, s[0:1]
	v_cvt_pk_bf16_f32 v114, v82, v83
	v_readfirstlane_b32 s98, v158
	v_readfirstlane_b32 s99, v159
	v_and_b32_e32 v244, 30, v137
	v_lshlrev_b32_e32 v244, 1, v244
	v_lshl_add_u32 v244, v136, 11, v244
	s_lshl_b32 s100, s23, 11
	s_add_u32 s98, s98, s100
	s_addc_u32 s99, s99, 0
	s_add_u32 s100, s98, 0x800
	s_addc_u32 s101, s99, 0
	global_store_dword v244, v114, s[100:101] offset:-2048
	v_mov_b32_e32 v82, v84
	v_mfma_f32_32x32x16_bf16 v[50:65], v[186:189], v[110:113], v[50:65]
	v_cndmask_b32_e64 v83, v82, v85, s[0:1]
	s_add_i32 s8, s8, -1
	s_add_i32 s82, s82, 1
	v_mov_b32_dpp v83, v83 quad_perm:[1,0,3,2] row_mask:0xf bank_mask:0xf bound_ctrl:1
	v_cndmask_b32_e64 v84, v85, v83, s[0:1]
	v_cndmask_b32_e64 v82, v83, v82, s[0:1]
	v_cvt_pk_bf16_f32 v84, v82, v84
	global_store_dword v244, v84, s[100:101] offset:2048
	v_mov_b32_e32 v82, v86
	v_mfma_f32_32x32x16_bf16 v[34:49], v[190:193], v[106:109], v[34:49]
	v_cndmask_b32_e64 v83, v82, v87, s[0:1]
	s_nop 1
	v_mov_b32_dpp v83, v83 quad_perm:[1,0,3,2] row_mask:0xf bank_mask:0xf bound_ctrl:1
	v_cndmask_b32_e64 v84, v87, v83, s[0:1]
	v_cndmask_b32_e64 v82, v83, v82, s[0:1]
	v_cvt_pk_bf16_f32 v84, v82, v84
	s_add_u32 s100, s98, 0x4800
	s_addc_u32 s101, s99, 0
	global_store_dword v244, v84, s[100:101] offset:-2048
	v_mov_b32_e32 v82, v89
; DI int crow(int r, int hi) { return (r & 3) + 8 * (r >> 2) + 4 * hi; }
; DI unsigned pkbf(float a, float b) { f32x2 v = {a, b}; bfx2 r = __builtin_convertvector(v, bfx2); return __builtin_bit_cast(unsigned, r); }
; DI void phase_gla_chain(const Params& P, int l, int task0, int ntask_stride, LAS unsigned char* lds) {
;     ...
;         __syncthreads();
;         CH_ISSUE(0, 0);
;         for (int n = 0; n < 64; ++n) {
;             const int b = n & 1;
;             if (n == 0) asm volatile("s_waitcnt vmcnt(0)" ::: "memory"); else asm volatile("s_waitcnt vmcnt(16)" ::: "memory");
;             __builtin_amdgcn_s_barrier();
;             asm volatile("" ::: "memory");
;             if (n + 1 < 64) CH_ISSUE(n + 1, b ^ 1);
;     ...
;             { const int cs = dir ? 63 - n : n; const size_t tokb = (size_t)sq * SEQL + cs * 64; const int odd = lane & 1;
;               bf16_t* ob = OFB + (size_t)dir * MTOK * 1024 + h * 256 + wid * 32 + (r32 & ~1);
; #pragma unroll
;               for (int ib = 0; ib < 2; ++ib)
; #pragma unroll
;                   for (int x = 0; x < 16; x += 2) { float ea_ = o[ib][x], eb_ = o[ib][x + 1]; asm volatile("" : "+v"(ea_), "+v"(eb_)); const float mine = odd ? eb_ : ea_, give = odd ? ea_ : eb_;
;                       const float got = __int_as_float(__builtin_amdgcn_update_dpp(0, __float_as_int(give), 0xB1, 0xF, 0xF, true));
;                       const unsigned w = odd ? pkbf(got, mine) : pkbf(mine, got);
;                       *(unsigned*)(ob + (tokb + ib * 32 + crow(x + odd, hi)) * 1024) = w; } }
	v_mfma_f32_32x32x16_bf16 v[50:65], v[194:197], v[106:109], v[50:65]
	v_cndmask_b32_e64 v83, v88, v82, s[0:1]
	s_nop 1
	v_mov_b32_dpp v83, v83 quad_perm:[1,0,3,2] row_mask:0xf bank_mask:0xf bound_ctrl:1
	v_cndmask_b32_e64 v82, v82, v83, s[0:1]
	v_cndmask_b32_e64 v83, v83, v88, s[0:1]
	v_cvt_pk_bf16_f32 v84, v83, v82
	global_store_dword v244, v84, s[100:101] offset:2048
	v_mov_b32_e32 v82, v90
	v_mfma_f32_32x32x16_bf16 v[34:49], v[204:207], v[102:105], v[34:49]
	v_cndmask_b32_e64 v83, v82, v91, s[0:1]
	s_nop 1
	v_mov_b32_dpp v83, v83 quad_perm:[1,0,3,2] row_mask:0xf bank_mask:0xf bound_ctrl:1
	v_cndmask_b32_e64 v84, v91, v83, s[0:1]
	v_cndmask_b32_e64 v82, v83, v82, s[0:1]
	v_cvt_pk_bf16_f32 v84, v82, v84
	s_add_u32 s100, s98, 0x8800
	s_addc_u32 s101, s99, 0
	global_store_dword v244, v84, s[100:101] offset:-2048
	v_mov_b32_e32 v82, v92
	v_mfma_f32_32x32x16_bf16 v[50:65], v[208:211], v[102:105], v[50:65]
	v_cndmask_b32_e64 v83, v82, v93, s[0:1]
	s_nop 1
	v_mov_b32_dpp v83, v83 quad_perm:[1,0,3,2] row_mask:0xf bank_mask:0xf bound_ctrl:1
	v_cndmask_b32_e64 v84, v93, v83, s[0:1]
	v_cndmask_b32_e64 v82, v83, v82, s[0:1]
	v_cvt_pk_bf16_f32 v84, v82, v84
	global_store_dword v244, v84, s[100:101] offset:2048
	v_mov_b32_e32 v82, v95
	v_mfma_f32_32x32x16_bf16 v[34:49], v[224:227], v[98:101], v[34:49]
	v_cndmask_b32_e64 v83, v94, v82, s[0:1]
	s_nop 1
	v_mov_b32_dpp v83, v83 quad_perm:[1,0,3,2] row_mask:0xf bank_mask:0xf bound_ctrl:1
	v_cndmask_b32_e64 v82, v82, v83, s[0:1]
	v_cndmask_b32_e64 v83, v83, v94, s[0:1]
	v_cvt_pk_bf16_f32 v84, v83, v82
	s_add_u32 s100, s98, 0xc800
	s_addc_u32 s101, s99, 0
	global_store_dword v244, v84, s[100:101] offset:-2048
	v_mov_b32_e32 v82, v96
	v_mfma_f32_32x32x16_bf16 v[50:65], v[228:231], v[98:101], v[50:65]
	v_cndmask_b32_e64 v83, v82, v97, s[0:1]
	s_nop 1
	v_mov_b32_dpp v83, v83 quad_perm:[1,0,3,2] row_mask:0xf bank_mask:0xf bound_ctrl:1
	v_cndmask_b32_e64 v84, v97, v83, s[0:1]
	v_cndmask_b32_e64 v82, v83, v82, s[0:1]
	v_cvt_pk_bf16_f32 v84, v82, v84
	global_store_dword v244, v84, s[100:101] offset:2048
	s_or_b32 s23, s23, 32
	v_cndmask_b32_e64 v82, v66, v67, s[0:1]
	s_nop 0
	v_mov_b32_dpp v82, v82 quad_perm:[1,0,3,2] row_mask:0xf bank_mask:0xf bound_ctrl:1
	v_cndmask_b32_e64 v67, v67, v82, s[0:1]
	v_cndmask_b32_e64 v66, v82, v66, s[0:1]
	v_cvt_pk_bf16_f32 v82, v66, v67
	s_add_u32 s100, s98, 0x10800
	s_addc_u32 s101, s99, 0
	global_store_dword v244, v82, s[100:101] offset:-2048
	v_mov_b32_e32 v66, v69
	s_nop 0
	v_cndmask_b32_e64 v67, v68, v66, s[0:1]
	s_nop 1
	v_mov_b32_dpp v67, v67 quad_perm:[1,0,3,2] row_mask:0xf bank_mask:0xf bound_ctrl:1
	v_cndmask_b32_e64 v66, v66, v67, s[0:1]
	v_cndmask_b32_e64 v67, v67, v68, s[0:1]
	v_cvt_pk_bf16_f32 v68, v67, v66
	global_store_dword v244, v68, s[100:101] offset:2048
	v_mov_b32_e32 v66, v70
	s_nop 0
	v_cndmask_b32_e64 v67, v66, v71, s[0:1]
	s_nop 1
	v_mov_b32_dpp v67, v67 quad_perm:[1,0,3,2] row_mask:0xf bank_mask:0xf bound_ctrl:1
	v_cndmask_b32_e64 v68, v71, v67, s[0:1]
	v_cndmask_b32_e64 v66, v67, v66, s[0:1]
	v_cvt_pk_bf16_f32 v68, v66, v68
	s_add_u32 s100, s98, 0x14800
	s_addc_u32 s101, s99, 0
	global_store_dword v244, v68, s[100:101] offset:-2048
	v_mov_b32_e32 v66, v72
	s_nop 0
	v_cndmask_b32_e64 v67, v66, v73, s[0:1]
	s_nop 1
	v_mov_b32_dpp v67, v67 quad_perm:[1,0,3,2] row_mask:0xf bank_mask:0xf bound_ctrl:1
	v_cndmask_b32_e64 v68, v73, v67, s[0:1]
	v_cndmask_b32_e64 v66, v67, v66, s[0:1]
	v_cvt_pk_bf16_f32 v68, v66, v68
	global_store_dword v244, v68, s[100:101] offset:2048
	v_mov_b32_e32 v66, v75
	s_nop 0
	v_cndmask_b32_e64 v67, v74, v66, s[0:1]
	s_nop 1
	v_mov_b32_dpp v67, v67 quad_perm:[1,0,3,2] row_mask:0xf bank_mask:0xf bound_ctrl:1
	v_cndmask_b32_e64 v66, v66, v67, s[0:1]
	v_cndmask_b32_e64 v67, v67, v74, s[0:1]
	v_cvt_pk_bf16_f32 v68, v67, v66
	s_add_u32 s100, s98, 0x18800
	s_addc_u32 s101, s99, 0
	global_store_dword v244, v68, s[100:101] offset:-2048
	v_mov_b32_e32 v66, v77
	s_nop 0
	v_cndmask_b32_e64 v67, v76, v66, s[0:1]
	s_nop 1
	v_mov_b32_dpp v67, v67 quad_perm:[1,0,3,2] row_mask:0xf bank_mask:0xf bound_ctrl:1
	v_cndmask_b32_e64 v66, v66, v67, s[0:1]
	v_cndmask_b32_e64 v67, v67, v76, s[0:1]
	v_cvt_pk_bf16_f32 v68, v67, v66
	global_store_dword v244, v68, s[100:101] offset:2048
	v_mov_b32_e32 v66, v78
	s_nop 0
	v_cndmask_b32_e64 v67, v66, v79, s[0:1]
	s_nop 1
	v_mov_b32_dpp v67, v67 quad_perm:[1,0,3,2] row_mask:0xf bank_mask:0xf bound_ctrl:1
	v_cndmask_b32_e64 v68, v79, v67, s[0:1]
	v_cndmask_b32_e64 v66, v67, v66, s[0:1]
	v_cvt_pk_bf16_f32 v68, v66, v68
	s_add_u32 s100, s98, 0x1c800
	s_addc_u32 s101, s99, 0
	global_store_dword v244, v68, s[100:101] offset:-2048
	v_mov_b32_e32 v66, v81
	s_nop 0
	v_cndmask_b32_e64 v67, v80, v66, s[0:1]
	s_nop 1
	v_mov_b32_dpp v67, v67 quad_perm:[1,0,3,2] row_mask:0xf bank_mask:0xf bound_ctrl:1
	v_cndmask_b32_e64 v66, v66, v67, s[0:1]
	v_cndmask_b32_e64 v67, v67, v80, s[0:1]
	v_cvt_pk_bf16_f32 v68, v67, v66
	global_store_dword v244, v68, s[100:101] offset:2048
	s_cmp_eq_u32 s8, -2
	s_cbranch_scc1 .LBB0_965
.LBB0_972:
	s_add_i32 s83, s82, -1
	s_waitcnt vmcnt(16)
	s_barrier
	s_and_b32 s84, s83, 1
	s_cmp_eq_u32 s8, -1
	s_cbranch_scc1 .LBB0_971
	s_and_b64 s[22:23], s[10:11], exec
	s_cselect_b32 s22, s82, s8
	s_add_i32 s22, s22, s81
	s_lshl_b32 s22, s22, 2
	s_or_b32 s86, s22, s80
	s_ashr_i32 s87, s86, 31
	s_add_u32 s22, s25, s86
	s_addc_u32 s23, 0, s87
	s_mul_i32 s64, s23, 0xa000
	s_mul_hi_u32 s65, s22, 0xa000
	s_add_i32 s65, s65, s64
	s_mul_i32 s64, s22, 0xa000
	s_add_u32 s64, s27, s64
	s_addc_u32 s65, s28, s65
	s_lshl_b64 s[86:87], s[86:87], 15
	s_add_u32 s66, s29, s86
	s_addc_u32 s67, s30, s87
	s_xor_b32 s68, s84, 1
	s_mul_i32 s68, s68, 0x12400
	s_add_i32 s85, s68, 0
	v_add_u32_e32 v245, 0x400, v134
	v_add_u32_e32 v246, 0x800, v134
	v_add_u32_e32 v247, 0xc00, v134
	v_add_u32_e32 v248, 0x1000, v134
	s_lshl_b32 s32, s31, 4
	s_lshl_b32 s98, s31, 2
	s_add_i32 s98, s98, s32
	s_add_u32 s100, s64, s98
	s_addc_u32 s101, s65, 0
	s_add_i32 s99, s85, s98
	s_add_u32 s88, s66, s32
	s_addc_u32 s89, s67, 0
	s_add_i32 s90, s85, s32
	s_and_b64 vcc, exec, s[2:3]
	s_cbranch_vccnz .LBB0_971
	s_add_i32 s64, s85, s31
	s_lshl_b64 s[22:23], s[22:23], 9
	s_add_i32 m0, s64, 0x12000
	v_lshl_add_u64 v[66:67], v[156:157], 0, s[22:23]
	global_load_lds_dword v[66:67], off
	s_branch .LBB0_971
